# XC phase setup: the two LDS staging loops (folded gate weights, conv taps/bias) issued as straight-line batches: 4+3 loads in flight and one wait instead of one global round trip per loop trip
# speedup vs baseline: 1.0148x; 1.0034x over previous
; #define LAS __attribute__((address_space(3)))
; DEV void xc_gates_phase(LAS char* shm, const bf16_t* mi, bf16_t* xc, const bf16_t* WfT, const float* cw, const float* cb, float* gpart  ) {
;     ...
;     for (int i = tid; i < 2 * 8 * 128; i += 512) {
;         const int rowi = i >> 7, pc = i & 127;
;         const uint4 v = *(const uint4*)(WfT + (size_t)((rowi >> 3) * 16 + (rowi & 7)) * 1024 + pc * 8);
;         *(LAS u32x4*)(shm + rowi * WRS + pc * 16) = (u32x4){v.x, v.y, v.z, v.w};
;     }
.LBB0_315:
	s_movk_i32 s20, 0x810
	v_add_u32_e32 v100, 0, v5
	v_ashrrev_i32_e32 v101, 7, v100
	v_ashrrev_i32_e32 v109, 6, v100
	v_and_b32_e32 v102, 7, v101
	v_and_or_b32 v102, v109, -16, v102
	v_ashrrev_i32_e32 v103, 31, v102
	v_lshlrev_b64 v[102:103], 11, v[102:103]
	v_lshl_add_u64 v[102:103], v[2:3], 0, v[102:103]
	global_load_dwordx4 v[104:107], v[102:103], off
	v_mad_u32_u24 v108, v101, s20, v4
	v_add_u32_e32 v112, 512, v5
	v_ashrrev_i32_e32 v113, 7, v112
	v_ashrrev_i32_e32 v121, 6, v112
	v_and_b32_e32 v114, 7, v113
	v_and_or_b32 v114, v121, -16, v114
	v_ashrrev_i32_e32 v115, 31, v114
	v_lshlrev_b64 v[114:115], 11, v[114:115]
	v_lshl_add_u64 v[114:115], v[2:3], 0, v[114:115]
	global_load_dwordx4 v[116:119], v[114:115], off
	v_mad_u32_u24 v120, v113, s20, v4
	v_add_u32_e32 v124, 1024, v5
	v_ashrrev_i32_e32 v125, 7, v124
	v_ashrrev_i32_e32 v133, 6, v124
	v_and_b32_e32 v126, 7, v125
	v_and_or_b32 v126, v133, -16, v126
	v_ashrrev_i32_e32 v127, 31, v126
	v_lshlrev_b64 v[126:127], 11, v[126:127]
	v_lshl_add_u64 v[126:127], v[2:3], 0, v[126:127]
	global_load_dwordx4 v[128:131], v[126:127], off
	v_mad_u32_u24 v132, v125, s20, v4
	v_add_u32_e32 v136, 1536, v5
	v_ashrrev_i32_e32 v137, 7, v136
	v_ashrrev_i32_e32 v145, 6, v136
	v_and_b32_e32 v138, 7, v137
	v_and_or_b32 v138, v145, -16, v138
	v_ashrrev_i32_e32 v139, 31, v138
	v_lshlrev_b64 v[138:139], 11, v[138:139]
	v_lshl_add_u64 v[138:139], v[2:3], 0, v[138:139]
	global_load_dwordx4 v[140:143], v[138:139], off
	v_mad_u32_u24 v144, v137, s20, v4
	s_waitcnt vmcnt(0)
	ds_write_b128 v108, v[104:107]
	ds_write_b128 v120, v[116:119]
	ds_write_b128 v132, v[128:131]
	ds_write_b128 v144, v[140:143]

; #define LAS __attribute__((address_space(3)))
; DEV void xc_gates_phase(LAS char* shm, const bf16_t* mi, bf16_t* xc, const bf16_t* WfT, const float* cw, const float* cb, float* gpart  ) {
;     ...
;     for (int i = tid; i < 5 * 256; i += 512) {
;         const float4 v = (i < 1024) ? *(const float4*)(cw + i * 4) : *(const float4*)(cb + (i - 1024) * 4);
;         *(LAS f32x4*)(shm + CWL + i * 16) = (f32x4){v.x, v.y, v.z, v.w};
;     }
.LBB0_318:
	v_ashrrev_i32_e32 v3, 31, v2
	v_lshl_add_u64 v[150:151], v[2:3], 2, s[6:7]
	global_load_dwordx4 v[152:155], v[150:151], off
	s_mov_b64 s[20:21], 0x2000
	v_lshl_add_u64 v[156:157], v[150:151], 0, s[20:21]
	global_load_dwordx4 v[158:161], v[156:157], off
	v_cmp_gt_i32_e32 vcc, 0x100, v5
	s_and_saveexec_b64 s[20:21], vcc
	v_add_u32_e32 v166, 0x1000, v2
	v_mov_b32_e32 v167, 0
	v_lshl_add_u64 v[156:157], v[166:167], 2, s[8:9]
	v_lshl_add_u64 v[156:157], v[156:157], 0, s[12:13]
	global_load_dwordx4 v[162:165], v[156:157], off
	s_or_b64 exec, exec, s[20:21]
	s_waitcnt vmcnt(0)
	ds_write_b128 v4, v[152:155]
	ds_write_b128 v4, v[158:161] offset:8192
	s_and_saveexec_b64 s[20:21], vcc
	ds_write_b128 v4, v[162:165] offset:16384
	s_or_b64 exec, exec, s[20:21]

; #define LAS __attribute__((address_space(3)))
; DEV void xc_gates_phase(LAS char* shm, const bf16_t* mi, bf16_t* xc, const bf16_t* WfT, const float* cw, const float* cb, float* gpart  ) {
;     ...
;     for (int i = tid; i < 5 * 256; i += 512) {
;         const float4 v = (i < 1024) ? *(const float4*)(cw + i * 4) : *(const float4*)(cb + (i - 1024) * 4);
;         *(LAS f32x4*)(shm + CWL + i * 16) = (f32x4){v.x, v.y, v.z, v.w};
;     }
.LBB0_1173:
	v_ashrrev_i32_e32 v3, 31, v2
	v_lshl_add_u64 v[150:151], v[2:3], 2, s[8:9]
	global_load_dwordx4 v[152:155], v[150:151], off
	s_mov_b64 s[20:21], 0x2000
	v_lshl_add_u64 v[156:157], v[150:151], 0, s[20:21]
	global_load_dwordx4 v[158:161], v[156:157], off
	v_cmp_gt_i32_e32 vcc, 0x100, v5
	s_and_saveexec_b64 s[20:21], vcc
	v_add_u32_e32 v166, 0x1000, v2
	v_mov_b32_e32 v167, 0
	v_lshl_add_u64 v[156:157], v[166:167], 2, s[4:5]
	v_lshl_add_u64 v[156:157], v[156:157], 0, s[12:13]
	global_load_dwordx4 v[162:165], v[156:157], off
	s_or_b64 exec, exec, s[20:21]
	s_waitcnt vmcnt(0)
	ds_write_b128 v4, v[152:155]
	ds_write_b128 v4, v[158:161] offset:8192
	s_and_saveexec_b64 s[20:21], vcc
	ds_write_b128 v4, v[162:165] offset:16384
	s_or_b64 exec, exec, s[20:21]
